# compress item epilogue: 24 serialized pe-bias loads replaced by 16 prefetched values with one wait
# baseline (speedup 1.0000x reference)
; DI void compress_item(const Params& p, int L, int item, char* smem) {
;     ...
;   if (wn == 0) {
; #pragma unroll
;     for (int mt = 0; mt < 2; ++mt)
; #pragma unroll
;       for (int nt = 0; nt < 2; ++nt)
; #pragma unroll
;         for (int i = 0; i < 16; ++i) {
;           const int rl = wm * 64 + mt * 32 + (i & 3) + 8 * (i >> 2) + 4 * hh;
;           const int n = nt * 32 + r;
;           float pb_ = 0.f;
; #pragma unroll
;           for (int q8 = 0; q8 < 8; ++q8) pb_ += p.pebias[(kv * 8 + q8) * 64 + n];
;           const float hsum = acc[mt][nt][i] + pb_;
;           Hs[rl * 65 + n] = hsum / (1.f + __expf(-hsum));
;         }
.LBB0_761:
	s_or_b64 exec, exec, s[8:9]
	v_and_b32_e32 v64, 64, v114
	v_cmp_eq_u32_e32 vcc, 0, v64
	v_ashrrev_i32_e32 v64, 1, v114
	s_and_saveexec_b64 s[8:9], vcc
	s_cbranch_execz .LBB0_763
	v_lshrrev_b32_e32 v65, 3, v114
	v_and_b32_e32 v66, 0x7c, v66
	v_readlane_b32 s16, v254, 30
	v_and_b32_e32 v67, 4, v65
	v_lshl_or_b32 v65, s12, 11, v66
	v_readlane_b32 s18, v254, 32
	v_readlane_b32 s19, v254, 33
	s_mov_b32 s12, 0x3fffffc0
	v_and_or_b32 v67, v64, s12, v67
	s_movk_i32 s12, 0x104
	v_mad_u64_u32 v[66:67], s[14:15], v67, s12, v[66:67]
	s_nop 0
	global_load_dword v76, v65, s[18:19]
	global_load_dword v77, v65, s[18:19] offset:128
	global_load_dword v78, v65, s[18:19] offset:256
	global_load_dword v79, v65, s[18:19] offset:384
	global_load_dword v80, v65, s[18:19] offset:512
	global_load_dword v81, v65, s[18:19] offset:640
	global_load_dword v82, v65, s[18:19] offset:768
	global_load_dword v83, v65, s[18:19] offset:896
	global_load_dword v84, v65, s[18:19] offset:1024
	global_load_dword v85, v65, s[18:19] offset:1152
	global_load_dword v86, v65, s[18:19] offset:1280
	global_load_dword v87, v65, s[18:19] offset:1408
	global_load_dword v88, v65, s[18:19] offset:1536
	global_load_dword v89, v65, s[18:19] offset:1664
	global_load_dword v90, v65, s[18:19] offset:1792
	global_load_dword v91, v65, s[18:19] offset:1920
	s_waitcnt vmcnt(0)
	v_mov_b32_e32 v68, v76
	v_mov_b32_e32 v69, v78
	v_readlane_b32 s17, v254, 31
	s_waitcnt vmcnt(1)
	v_add_f32_e32 v68, 0, v68
	s_waitcnt vmcnt(0)
	v_add_f32_e32 v68, v68, v69
	v_mov_b32_e32 v69, v80
	s_waitcnt vmcnt(0)
	v_add_f32_e32 v68, v68, v69
	v_mov_b32_e32 v69, v82
	s_waitcnt vmcnt(0)
	v_add_f32_e32 v68, v68, v69
	v_mov_b32_e32 v69, v84
	s_waitcnt vmcnt(0)
	v_add_f32_e32 v68, v68, v69
	v_mov_b32_e32 v69, v86
	s_waitcnt vmcnt(0)
	v_add_f32_e32 v68, v68, v69
	v_mov_b32_e32 v69, v88
	s_waitcnt vmcnt(0)
	v_add_f32_e32 v68, v68, v69
	v_mov_b32_e32 v69, v90
	s_waitcnt vmcnt(0)
	v_add_f32_e32 v68, v68, v69
	v_add_f32_e32 v48, v48, v68
	v_mul_f32_e32 v69, 0xbfb8aa3b, v48
	v_exp_f32_e32 v69, v69
	v_add_f32_e32 v16, v16, v68
	v_add_f32_e32 v69, 1.0, v69
	v_div_scale_f32 v70, s[14:15], v69, v69, v48
	v_rcp_f32_e32 v71, v70
	s_nop 0
	v_fma_f32 v72, -v70, v71, 1.0
	v_fmac_f32_e32 v71, v72, v71
	v_div_scale_f32 v72, vcc, v48, v69, v48
	v_mul_f32_e32 v73, v72, v71
	v_fma_f32 v74, -v70, v73, v72
	v_fmac_f32_e32 v73, v74, v71
	v_fma_f32 v70, -v70, v73, v72
	v_div_fmas_f32 v70, v70, v71, v73
	v_div_fixup_f32 v73, v70, v69, v48
	v_add_f32_e32 v48, v49, v68
	v_mul_f32_e32 v49, 0xbfb8aa3b, v48
	v_exp_f32_e32 v49, v49
	s_nop 0
	v_add_f32_e32 v49, 1.0, v49
	v_div_scale_f32 v67, s[14:15], v49, v49, v48
	v_rcp_f32_e32 v69, v67
	s_nop 0
	v_fma_f32 v70, -v67, v69, 1.0
	v_fmac_f32_e32 v69, v70, v69
	v_div_scale_f32 v70, vcc, v48, v49, v48
	v_mul_f32_e32 v71, v70, v69
	v_fma_f32 v72, -v67, v71, v70
	v_fmac_f32_e32 v71, v72, v69
	v_fma_f32 v67, -v67, v71, v70
	v_div_fmas_f32 v67, v67, v69, v71
	v_div_fixup_f32 v75, v67, v49, v48
	v_add_f32_e32 v48, v50, v68
	v_mul_f32_e32 v49, 0xbfb8aa3b, v48
	v_exp_f32_e32 v49, v49
	s_nop 0
	v_add_f32_e32 v49, 1.0, v49
	v_div_scale_f32 v50, s[14:15], v49, v49, v48
	v_rcp_f32_e32 v67, v50
	s_nop 0
	v_fma_f32 v69, -v50, v67, 1.0
	v_fmac_f32_e32 v67, v69, v67
	v_div_scale_f32 v69, vcc, v48, v49, v48
	v_mul_f32_e32 v70, v69, v67
	v_fma_f32 v71, -v50, v70, v69
	v_fmac_f32_e32 v70, v71, v67
	v_fma_f32 v50, -v50, v70, v69
	v_div_fmas_f32 v50, v50, v67, v70
	v_div_fixup_f32 v74, v50, v49, v48
	v_add_f32_e32 v48, v51, v68
	v_mul_f32_e32 v49, 0xbfb8aa3b, v48
	v_exp_f32_e32 v49, v49
	s_nop 0
	v_add_f32_e32 v49, 1.0, v49
	v_div_scale_f32 v50, s[14:15], v49, v49, v48
	v_rcp_f32_e32 v51, v50
	s_nop 0
	v_fma_f32 v67, -v50, v51, 1.0
	v_fmac_f32_e32 v51, v67, v51
	v_div_scale_f32 v67, vcc, v48, v49, v48
	v_mul_f32_e32 v69, v67, v51
	v_fma_f32 v70, -v50, v69, v67
	v_fmac_f32_e32 v69, v70, v51
	v_fma_f32 v50, -v50, v69, v67
	v_div_fmas_f32 v50, v50, v51, v69
	v_div_fixup_f32 v72, v50, v49, v48
	v_add_f32_e32 v48, v52, v68
	v_mul_f32_e32 v49, 0xbfb8aa3b, v48
	v_exp_f32_e32 v49, v49
	s_nop 0
	v_add_f32_e32 v49, 1.0, v49
	v_div_scale_f32 v50, s[14:15], v49, v49, v48
	v_rcp_f32_e32 v51, v50
	s_nop 0
	v_fma_f32 v52, -v50, v51, 1.0
	v_fmac_f32_e32 v51, v52, v51
	v_div_scale_f32 v52, vcc, v48, v49, v48
	v_mul_f32_e32 v67, v52, v51
	v_fma_f32 v69, -v50, v67, v52
	v_fmac_f32_e32 v67, v69, v51
	v_fma_f32 v50, -v50, v67, v52
	v_div_fmas_f32 v50, v50, v51, v67
	v_div_fixup_f32 v71, v50, v49, v48
	v_add_f32_e32 v48, v53, v68
	v_mul_f32_e32 v49, 0xbfb8aa3b, v48
	v_exp_f32_e32 v49, v49
	s_nop 0
	v_add_f32_e32 v49, 1.0, v49
	v_div_scale_f32 v50, s[14:15], v49, v49, v48
	v_rcp_f32_e32 v51, v50
	s_nop 0
	v_fma_f32 v52, -v50, v51, 1.0
	v_fmac_f32_e32 v51, v52, v51
	v_div_scale_f32 v52, vcc, v48, v49, v48
	v_mul_f32_e32 v53, v52, v51
	v_fma_f32 v67, -v50, v53, v52
	v_fmac_f32_e32 v53, v67, v51
	v_fma_f32 v50, -v50, v53, v52
	v_div_fmas_f32 v50, v50, v51, v53
	v_div_fixup_f32 v70, v50, v49, v48
	v_add_f32_e32 v48, v54, v68
	v_mul_f32_e32 v49, 0xbfb8aa3b, v48
	v_exp_f32_e32 v49, v49
	s_nop 0
	v_add_f32_e32 v49, 1.0, v49
	v_div_scale_f32 v50, s[14:15], v49, v49, v48
	v_rcp_f32_e32 v51, v50
	s_nop 0
	v_fma_f32 v52, -v50, v51, 1.0
	v_fmac_f32_e32 v51, v52, v51
	v_div_scale_f32 v52, vcc, v48, v49, v48
	v_mul_f32_e32 v53, v52, v51
	v_fma_f32 v54, -v50, v53, v52
	v_fmac_f32_e32 v53, v54, v51
	v_fma_f32 v50, -v50, v53, v52
	v_div_fmas_f32 v50, v50, v51, v53
	v_div_fixup_f32 v69, v50, v49, v48
	v_add_f32_e32 v48, v55, v68
	v_mul_f32_e32 v49, 0xbfb8aa3b, v48
	v_exp_f32_e32 v49, v49
	s_nop 0
	v_add_f32_e32 v49, 1.0, v49
	v_div_scale_f32 v50, s[14:15], v49, v49, v48
; DI void compress_item(const Params& p, int L, int item, char* smem) {
;     ...
;         for (int i = 0; i < 16; ++i) {
;           const int rl = wm * 64 + mt * 32 + (i & 3) + 8 * (i >> 2) + 4 * hh;
;           const int n = nt * 32 + r;
;           float pb_ = 0.f;
; #pragma unroll
;           for (int q8 = 0; q8 < 8; ++q8) pb_ += p.pebias[(kv * 8 + q8) * 64 + n];
;           const float hsum = acc[mt][nt][i] + pb_;
;           Hs[rl * 65 + n] = hsum / (1.f + __expf(-hsum));
;         }
	v_rcp_f32_e32 v51, v50
	s_nop 0
	v_fma_f32 v52, -v50, v51, 1.0
	v_fmac_f32_e32 v51, v52, v51
	v_div_scale_f32 v52, vcc, v48, v49, v48
	v_mul_f32_e32 v53, v52, v51
	v_fma_f32 v54, -v50, v53, v52
	v_fmac_f32_e32 v53, v54, v51
	v_fma_f32 v50, -v50, v53, v52
	v_div_fmas_f32 v50, v50, v51, v53
	v_div_fixup_f32 v67, v50, v49, v48
	v_add_f32_e32 v48, v56, v68
	v_mul_f32_e32 v49, 0xbfb8aa3b, v48
	v_exp_f32_e32 v49, v49
	s_nop 0
	v_add_f32_e32 v49, 1.0, v49
	v_div_scale_f32 v50, s[14:15], v49, v49, v48
	v_rcp_f32_e32 v51, v50
	s_nop 0
	v_fma_f32 v52, -v50, v51, 1.0
	v_fmac_f32_e32 v51, v52, v51
	v_div_scale_f32 v52, vcc, v48, v49, v48
	v_mul_f32_e32 v53, v52, v51
	v_fma_f32 v54, -v50, v53, v52
	v_fmac_f32_e32 v53, v54, v51
	v_fma_f32 v50, -v50, v53, v52
	v_div_fmas_f32 v50, v50, v51, v53
	v_div_fixup_f32 v56, v50, v49, v48
	v_add_f32_e32 v48, v57, v68
	v_mul_f32_e32 v49, 0xbfb8aa3b, v48
	v_exp_f32_e32 v49, v49
	s_nop 0
	v_add_f32_e32 v49, 1.0, v49
	v_div_scale_f32 v50, s[14:15], v49, v49, v48
	v_rcp_f32_e32 v51, v50
	s_nop 0
	v_fma_f32 v52, -v50, v51, 1.0
	v_fmac_f32_e32 v51, v52, v51
	v_div_scale_f32 v52, vcc, v48, v49, v48
	v_mul_f32_e32 v53, v52, v51
	v_fma_f32 v54, -v50, v53, v52
	v_fmac_f32_e32 v53, v54, v51
	v_fma_f32 v50, -v50, v53, v52
	v_div_fmas_f32 v50, v50, v51, v53
	v_div_fixup_f32 v55, v50, v49, v48
	v_add_f32_e32 v48, v58, v68
	v_mul_f32_e32 v49, 0xbfb8aa3b, v48
	v_exp_f32_e32 v49, v49
	s_nop 0
	v_add_f32_e32 v49, 1.0, v49
	v_div_scale_f32 v50, s[14:15], v49, v49, v48
	v_rcp_f32_e32 v51, v50
	s_nop 0
	v_fma_f32 v52, -v50, v51, 1.0
	v_fmac_f32_e32 v51, v52, v51
	v_div_scale_f32 v52, vcc, v48, v49, v48
	v_mul_f32_e32 v53, v52, v51
	v_fma_f32 v54, -v50, v53, v52
	v_fmac_f32_e32 v53, v54, v51
	v_fma_f32 v50, -v50, v53, v52
	v_div_fmas_f32 v50, v50, v51, v53
	v_div_fixup_f32 v54, v50, v49, v48
	v_add_f32_e32 v48, v59, v68
	v_mul_f32_e32 v49, 0xbfb8aa3b, v48
	v_exp_f32_e32 v49, v49
	s_nop 0
	v_add_f32_e32 v49, 1.0, v49
	v_div_scale_f32 v50, s[14:15], v49, v49, v48
	v_rcp_f32_e32 v51, v50
	s_nop 0
	v_fma_f32 v52, -v50, v51, 1.0
	v_fmac_f32_e32 v51, v52, v51
	v_div_scale_f32 v52, vcc, v48, v49, v48
	v_mul_f32_e32 v53, v52, v51
	v_fma_f32 v57, -v50, v53, v52
	v_fmac_f32_e32 v53, v57, v51
	v_fma_f32 v50, -v50, v53, v52
	v_div_fmas_f32 v50, v50, v51, v53
	v_div_fixup_f32 v53, v50, v49, v48
	v_add_f32_e32 v48, v60, v68
	v_mul_f32_e32 v49, 0xbfb8aa3b, v48
	v_exp_f32_e32 v49, v49
	s_nop 0
	v_add_f32_e32 v49, 1.0, v49
	v_div_scale_f32 v50, s[14:15], v49, v49, v48
	v_rcp_f32_e32 v51, v50
	s_nop 0
	v_fma_f32 v52, -v50, v51, 1.0
	v_fmac_f32_e32 v51, v52, v51
	v_div_scale_f32 v52, vcc, v48, v49, v48
	v_mul_f32_e32 v57, v52, v51
	v_fma_f32 v58, -v50, v57, v52
	v_fmac_f32_e32 v57, v58, v51
	v_fma_f32 v50, -v50, v57, v52
	v_div_fmas_f32 v50, v50, v51, v57
	v_div_fixup_f32 v52, v50, v49, v48
	v_add_f32_e32 v48, v61, v68
	v_mul_f32_e32 v49, 0xbfb8aa3b, v48
	v_exp_f32_e32 v49, v49
	s_nop 0
	v_add_f32_e32 v49, 1.0, v49
	v_div_scale_f32 v50, s[14:15], v49, v49, v48
	v_rcp_f32_e32 v51, v50
	s_nop 0
	v_fma_f32 v57, -v50, v51, 1.0
	v_fmac_f32_e32 v51, v57, v51
	v_div_scale_f32 v57, vcc, v48, v49, v48
	v_mul_f32_e32 v58, v57, v51
	v_fma_f32 v59, -v50, v58, v57
	v_fmac_f32_e32 v58, v59, v51
	v_fma_f32 v50, -v50, v58, v57
	v_div_fmas_f32 v50, v50, v51, v58
	v_div_fixup_f32 v51, v50, v49, v48
	v_add_f32_e32 v48, v62, v68
	v_mul_f32_e32 v49, 0xbfb8aa3b, v48
	v_exp_f32_e32 v49, v49
	s_nop 0
	v_add_f32_e32 v49, 1.0, v49
	v_div_scale_f32 v50, s[14:15], v49, v49, v48
	v_rcp_f32_e32 v57, v50
	s_nop 0
	v_fma_f32 v58, -v50, v57, 1.0
	v_fmac_f32_e32 v57, v58, v57
	v_div_scale_f32 v58, vcc, v48, v49, v48
	v_mul_f32_e32 v59, v58, v57
	v_fma_f32 v60, -v50, v59, v58
	v_fmac_f32_e32 v59, v60, v57
	v_fma_f32 v50, -v50, v59, v58
	v_div_fmas_f32 v50, v50, v57, v59
	v_div_fixup_f32 v50, v50, v49, v48
	v_add_f32_e32 v48, v63, v68
	v_mul_f32_e32 v49, 0xbfb8aa3b, v48
	v_exp_f32_e32 v49, v49
	s_nop 0
	v_add_f32_e32 v49, 1.0, v49
	v_div_scale_f32 v57, s[14:15], v49, v49, v48
	v_rcp_f32_e32 v58, v57
	s_nop 0
	v_fma_f32 v59, -v57, v58, 1.0
	v_fmac_f32_e32 v58, v59, v58
	v_div_scale_f32 v59, vcc, v48, v49, v48
	v_mul_f32_e32 v60, v59, v58
	v_fma_f32 v61, -v57, v60, v59
	v_fmac_f32_e32 v60, v61, v58
	v_fma_f32 v57, -v57, v60, v59
	v_div_fmas_f32 v57, v57, v58, v60
	v_div_fixup_f32 v49, v57, v49, v48
	v_mov_b32_e32 v48, v77
	v_mov_b32_e32 v57, v79
	v_mov_b32_e32 v58, v85
	s_waitcnt vmcnt(2)
	v_add_f32_e32 v48, 0, v48
	s_waitcnt vmcnt(1)
	v_add_f32_e32 v48, v48, v57
	v_mov_b32_e32 v57, v81
	s_waitcnt vmcnt(0)
	v_add_f32_e32 v48, v48, v57
	v_mov_b32_e32 v57, v83
	s_waitcnt vmcnt(0)
	v_add_f32_e32 v57, v48, v57
	v_add_f32_e32 v57, v57, v58
	v_mov_b32_e32 v58, v87
	s_waitcnt vmcnt(0)
	v_add_f32_e32 v57, v57, v58
	v_mov_b32_e32 v58, v89
	s_waitcnt vmcnt(0)
	v_add_f32_e32 v57, v57, v58
	v_mov_b32_e32 v58, v91
	s_waitcnt vmcnt(0)
; DI void compress_item(const Params& p, int L, int item, char* smem) {
;     ...
;         for (int i = 0; i < 16; ++i) {
;           const int rl = wm * 64 + mt * 32 + (i & 3) + 8 * (i >> 2) + 4 * hh;
;           const int n = nt * 32 + r;
;           float pb_ = 0.f;
; #pragma unroll
;           for (int q8 = 0; q8 < 8; ++q8) pb_ += p.pebias[(kv * 8 + q8) * 64 + n];
;           const float hsum = acc[mt][nt][i] + pb_;
;           Hs[rl * 65 + n] = hsum / (1.f + __expf(-hsum));
;         }
	v_add_f32_e32 v57, v57, v58
	v_add_f32_e32 v32, v32, v57
	v_mul_f32_e32 v58, 0xbfb8aa3b, v32
	v_exp_f32_e32 v58, v58
	v_add_f32_e32 v0, v0, v57
	v_add_f32_e32 v58, 1.0, v58
	v_div_scale_f32 v59, s[14:15], v58, v58, v32
	v_rcp_f32_e32 v60, v59
	s_nop 0
	v_fma_f32 v61, -v59, v60, 1.0
	v_fmac_f32_e32 v60, v61, v60
	v_div_scale_f32 v61, vcc, v32, v58, v32
	v_mul_f32_e32 v62, v61, v60
	v_fma_f32 v63, -v59, v62, v61
	v_fmac_f32_e32 v62, v63, v60
	v_fma_f32 v59, -v59, v62, v61
	v_div_fmas_f32 v59, v59, v60, v62
	v_div_fixup_f32 v32, v59, v58, v32
	ds_write2_b32 v66, v73, v32 offset1:32
	v_add_f32_e32 v32, v33, v57
	v_mul_f32_e32 v33, 0xbfb8aa3b, v32
	v_exp_f32_e32 v33, v33
	s_nop 0
	v_add_f32_e32 v33, 1.0, v33
	v_div_scale_f32 v58, s[14:15], v33, v33, v32
	v_rcp_f32_e32 v59, v58
	s_nop 0
	v_fma_f32 v60, -v58, v59, 1.0
	v_fmac_f32_e32 v59, v60, v59
	v_div_scale_f32 v60, vcc, v32, v33, v32
	v_mul_f32_e32 v61, v60, v59
	v_fma_f32 v62, -v58, v61, v60
	v_fmac_f32_e32 v61, v62, v59
	v_fma_f32 v58, -v58, v61, v60
	v_div_fmas_f32 v58, v58, v59, v61
	v_div_fixup_f32 v32, v58, v33, v32
	ds_write2_b32 v66, v75, v32 offset0:65 offset1:97
	v_add_f32_e32 v32, v34, v57
	v_mul_f32_e32 v33, 0xbfb8aa3b, v32
	v_exp_f32_e32 v33, v33
	s_nop 0
	v_add_f32_e32 v33, 1.0, v33
	v_div_scale_f32 v34, s[14:15], v33, v33, v32
	v_rcp_f32_e32 v58, v34
	s_nop 0
	v_fma_f32 v59, -v34, v58, 1.0
	v_fmac_f32_e32 v58, v59, v58
	v_div_scale_f32 v59, vcc, v32, v33, v32
	v_mul_f32_e32 v60, v59, v58
	v_fma_f32 v61, -v34, v60, v59
	v_fmac_f32_e32 v60, v61, v58
	v_fma_f32 v34, -v34, v60, v59
	v_div_fmas_f32 v34, v34, v58, v60
	v_div_fixup_f32 v32, v34, v33, v32
	ds_write2_b32 v66, v74, v32 offset0:130 offset1:162
	v_add_f32_e32 v32, v35, v57
	v_mul_f32_e32 v33, 0xbfb8aa3b, v32
	v_exp_f32_e32 v33, v33
	s_nop 0
	v_add_f32_e32 v33, 1.0, v33
	v_div_scale_f32 v34, s[14:15], v33, v33, v32
	v_rcp_f32_e32 v35, v34
	s_nop 0
	v_fma_f32 v58, -v34, v35, 1.0
	v_fmac_f32_e32 v35, v58, v35
	v_div_scale_f32 v58, vcc, v32, v33, v32
	v_mul_f32_e32 v59, v58, v35
	v_fma_f32 v60, -v34, v59, v58
	v_fmac_f32_e32 v59, v60, v35
	v_fma_f32 v34, -v34, v59, v58
	v_div_fmas_f32 v34, v34, v35, v59
	v_div_fixup_f32 v32, v34, v33, v32
	ds_write2_b32 v66, v72, v32 offset0:195 offset1:227
	v_add_f32_e32 v32, v36, v57
	v_mul_f32_e32 v33, 0xbfb8aa3b, v32
	v_exp_f32_e32 v33, v33
	s_nop 0
	v_add_f32_e32 v33, 1.0, v33
	v_div_scale_f32 v34, s[14:15], v33, v33, v32
	v_rcp_f32_e32 v35, v34
	s_nop 0
	v_fma_f32 v36, -v34, v35, 1.0
	v_fmac_f32_e32 v35, v36, v35
	v_div_scale_f32 v36, vcc, v32, v33, v32
	v_mul_f32_e32 v58, v36, v35
	v_fma_f32 v59, -v34, v58, v36
	v_fmac_f32_e32 v58, v59, v35
	v_fma_f32 v34, -v34, v58, v36
	v_div_fmas_f32 v34, v34, v35, v58
	v_div_fixup_f32 v32, v34, v33, v32
	v_add_u32_e32 v33, 0x800, v66
	ds_write2_b32 v33, v71, v32 offset0:8 offset1:40
	v_add_f32_e32 v32, v37, v57
	v_mul_f32_e32 v34, 0xbfb8aa3b, v32
	v_exp_f32_e32 v34, v34
	s_nop 0
	v_add_f32_e32 v34, 1.0, v34
	v_div_scale_f32 v35, s[14:15], v34, v34, v32
	v_rcp_f32_e32 v36, v35
	s_nop 0
	v_fma_f32 v37, -v35, v36, 1.0
	v_fmac_f32_e32 v36, v37, v36
	v_div_scale_f32 v37, vcc, v32, v34, v32
	v_mul_f32_e32 v58, v37, v36
	v_fma_f32 v59, -v35, v58, v37
	v_fmac_f32_e32 v58, v59, v36
	v_fma_f32 v35, -v35, v58, v37
	v_div_fmas_f32 v35, v35, v36, v58
	v_div_fixup_f32 v32, v35, v34, v32
	ds_write2_b32 v33, v70, v32 offset0:73 offset1:105
	v_add_f32_e32 v32, v38, v57
	v_mul_f32_e32 v34, 0xbfb8aa3b, v32
	v_exp_f32_e32 v34, v34
	s_nop 0
	v_add_f32_e32 v34, 1.0, v34
	v_div_scale_f32 v35, s[14:15], v34, v34, v32
	v_rcp_f32_e32 v36, v35
	s_nop 0
	v_fma_f32 v37, -v35, v36, 1.0
	v_fmac_f32_e32 v36, v37, v36
	v_div_scale_f32 v37, vcc, v32, v34, v32
	v_mul_f32_e32 v38, v37, v36
	v_fma_f32 v58, -v35, v38, v37
	v_fmac_f32_e32 v38, v58, v36
	v_fma_f32 v35, -v35, v38, v37
	v_div_fmas_f32 v35, v35, v36, v38
	v_div_fixup_f32 v32, v35, v34, v32
	ds_write2_b32 v33, v69, v32 offset0:138 offset1:170
	v_add_f32_e32 v32, v39, v57
	v_mul_f32_e32 v34, 0xbfb8aa3b, v32
	v_exp_f32_e32 v34, v34
	s_nop 0
	v_add_f32_e32 v34, 1.0, v34
	v_div_scale_f32 v35, s[14:15], v34, v34, v32
	v_rcp_f32_e32 v36, v35
	s_nop 0
	v_fma_f32 v37, -v35, v36, 1.0
	v_fmac_f32_e32 v36, v37, v36
	v_div_scale_f32 v37, vcc, v32, v34, v32
	v_mul_f32_e32 v38, v37, v36
	v_fma_f32 v39, -v35, v38, v37
	v_fmac_f32_e32 v38, v39, v36
	v_fma_f32 v35, -v35, v38, v37
	v_div_fmas_f32 v35, v35, v36, v38
	v_div_fixup_f32 v32, v35, v34, v32
	ds_write2_b32 v33, v67, v32 offset0:203 offset1:235
	v_add_f32_e32 v32, v40, v57
	v_mul_f32_e32 v33, 0xbfb8aa3b, v32
	v_exp_f32_e32 v33, v33
	s_nop 0
	v_add_f32_e32 v33, 1.0, v33
	v_div_scale_f32 v34, s[14:15], v33, v33, v32
	v_rcp_f32_e32 v35, v34
	s_nop 0
	v_fma_f32 v36, -v34, v35, 1.0
	v_fmac_f32_e32 v35, v36, v35
	v_div_scale_f32 v36, vcc, v32, v33, v32
	v_mul_f32_e32 v37, v36, v35
	v_fma_f32 v38, -v34, v37, v36
	v_fmac_f32_e32 v37, v38, v35
	v_fma_f32 v34, -v34, v37, v36
	v_div_fmas_f32 v34, v34, v35, v37
	v_div_fixup_f32 v32, v34, v33, v32
	v_add_u32_e32 v33, 0x1000, v66
	ds_write2_b32 v33, v56, v32 offset0:16 offset1:48
	v_add_f32_e32 v32, v41, v57
	v_mul_f32_e32 v34, 0xbfb8aa3b, v32
	v_exp_f32_e32 v34, v34
	s_nop 0
	v_add_f32_e32 v34, 1.0, v34
	v_div_scale_f32 v35, s[14:15], v34, v34, v32
	v_rcp_f32_e32 v36, v35
	s_nop 0
	v_fma_f32 v37, -v35, v36, 1.0
	v_fmac_f32_e32 v36, v37, v36
	v_div_scale_f32 v37, vcc, v32, v34, v32
	v_mul_f32_e32 v38, v37, v36
	v_fma_f32 v39, -v35, v38, v37
	v_fmac_f32_e32 v38, v39, v36
	v_fma_f32 v35, -v35, v38, v37
	v_div_fmas_f32 v35, v35, v36, v38
	v_div_fixup_f32 v32, v35, v34, v32
	ds_write2_b32 v33, v55, v32 offset0:81 offset1:113
	v_add_f32_e32 v32, v42, v57
; DI void compress_item(const Params& p, int L, int item, char* smem) {
;     ...
;         for (int i = 0; i < 16; ++i) {
;           const int rl = wm * 64 + mt * 32 + (i & 3) + 8 * (i >> 2) + 4 * hh;
;           const int n = nt * 32 + r;
;           float pb_ = 0.f;
; #pragma unroll
;           for (int q8 = 0; q8 < 8; ++q8) pb_ += p.pebias[(kv * 8 + q8) * 64 + n];
;           const float hsum = acc[mt][nt][i] + pb_;
;           Hs[rl * 65 + n] = hsum / (1.f + __expf(-hsum));
;         }
	v_mul_f32_e32 v34, 0xbfb8aa3b, v32
	v_exp_f32_e32 v34, v34
	s_nop 0
	v_add_f32_e32 v34, 1.0, v34
	v_div_scale_f32 v35, s[14:15], v34, v34, v32
	v_rcp_f32_e32 v36, v35
	s_nop 0
	v_fma_f32 v37, -v35, v36, 1.0
	v_fmac_f32_e32 v36, v37, v36
	v_div_scale_f32 v37, vcc, v32, v34, v32
	v_mul_f32_e32 v38, v37, v36
	v_fma_f32 v39, -v35, v38, v37
	v_fmac_f32_e32 v38, v39, v36
	v_fma_f32 v35, -v35, v38, v37
	v_div_fmas_f32 v35, v35, v36, v38
	v_div_fixup_f32 v32, v35, v34, v32
	ds_write2_b32 v33, v54, v32 offset0:146 offset1:178
	v_add_f32_e32 v32, v43, v57
	v_mul_f32_e32 v34, 0xbfb8aa3b, v32
	v_exp_f32_e32 v34, v34
	s_nop 0
	v_add_f32_e32 v34, 1.0, v34
	v_div_scale_f32 v35, s[14:15], v34, v34, v32
	v_rcp_f32_e32 v36, v35
	s_nop 0
	v_fma_f32 v37, -v35, v36, 1.0
	v_fmac_f32_e32 v36, v37, v36
	v_div_scale_f32 v37, vcc, v32, v34, v32
	v_mul_f32_e32 v38, v37, v36
	v_fma_f32 v39, -v35, v38, v37
	v_fmac_f32_e32 v38, v39, v36
	v_fma_f32 v35, -v35, v38, v37
	v_div_fmas_f32 v35, v35, v36, v38
	v_div_fixup_f32 v32, v35, v34, v32
	ds_write2_b32 v33, v53, v32 offset0:211 offset1:243
	v_add_f32_e32 v32, v44, v57
	v_mul_f32_e32 v33, 0xbfb8aa3b, v32
	v_exp_f32_e32 v33, v33
	s_nop 0
	v_add_f32_e32 v33, 1.0, v33
	v_div_scale_f32 v34, s[14:15], v33, v33, v32
	v_rcp_f32_e32 v35, v34
	s_nop 0
	v_fma_f32 v36, -v34, v35, 1.0
	v_fmac_f32_e32 v35, v36, v35
	v_div_scale_f32 v36, vcc, v32, v33, v32
	v_mul_f32_e32 v37, v36, v35
	v_fma_f32 v38, -v34, v37, v36
	v_fmac_f32_e32 v37, v38, v35
	v_fma_f32 v34, -v34, v37, v36
	v_div_fmas_f32 v34, v34, v35, v37
	v_div_fixup_f32 v32, v34, v33, v32
	v_add_u32_e32 v33, 0x1800, v66
	ds_write2_b32 v33, v52, v32 offset0:24 offset1:56
	v_add_f32_e32 v32, v45, v57
	v_mul_f32_e32 v34, 0xbfb8aa3b, v32
	v_exp_f32_e32 v34, v34
	s_nop 0
	v_add_f32_e32 v34, 1.0, v34
	v_div_scale_f32 v35, s[14:15], v34, v34, v32
	v_rcp_f32_e32 v36, v35
	s_nop 0
	v_fma_f32 v37, -v35, v36, 1.0
	v_fmac_f32_e32 v36, v37, v36
	v_div_scale_f32 v37, vcc, v32, v34, v32
	v_mul_f32_e32 v38, v37, v36
	v_fma_f32 v39, -v35, v38, v37
	v_fmac_f32_e32 v38, v39, v36
	v_fma_f32 v35, -v35, v38, v37
	v_div_fmas_f32 v35, v35, v36, v38
	v_div_fixup_f32 v32, v35, v34, v32
	ds_write2_b32 v33, v51, v32 offset0:89 offset1:121
	v_add_f32_e32 v32, v46, v57
	v_mul_f32_e32 v34, 0xbfb8aa3b, v32
	v_exp_f32_e32 v34, v34
	s_nop 0
	v_add_f32_e32 v34, 1.0, v34
	v_div_scale_f32 v35, s[14:15], v34, v34, v32
	v_rcp_f32_e32 v36, v35
	s_nop 0
	v_fma_f32 v37, -v35, v36, 1.0
	v_fmac_f32_e32 v36, v37, v36
	v_div_scale_f32 v37, vcc, v32, v34, v32
	v_mul_f32_e32 v38, v37, v36
	v_fma_f32 v39, -v35, v38, v37
	v_fmac_f32_e32 v38, v39, v36
	v_fma_f32 v35, -v35, v38, v37
	v_div_fmas_f32 v35, v35, v36, v38
	v_div_fixup_f32 v32, v35, v34, v32
	ds_write2_b32 v33, v50, v32 offset0:154 offset1:186
	v_add_f32_e32 v32, v47, v57
	v_mul_f32_e32 v34, 0xbfb8aa3b, v32
	v_exp_f32_e32 v34, v34
	s_nop 0
	v_add_f32_e32 v34, 1.0, v34
	v_div_scale_f32 v35, s[14:15], v34, v34, v32
	v_rcp_f32_e32 v36, v35
	s_nop 0
	v_fma_f32 v37, -v35, v36, 1.0
	v_fmac_f32_e32 v36, v37, v36
	v_div_scale_f32 v37, vcc, v32, v34, v32
	v_mul_f32_e32 v38, v37, v36
	v_fma_f32 v39, -v35, v38, v37
	v_fmac_f32_e32 v38, v39, v36
	v_fma_f32 v35, -v35, v38, v37
	v_div_fmas_f32 v35, v35, v36, v38
	v_div_fixup_f32 v32, v35, v34, v32
	ds_write2_b32 v33, v49, v32 offset0:219 offset1:251
	v_mul_f32_e32 v32, 0xbfb8aa3b, v16
	v_exp_f32_e32 v32, v32
	s_nop 0
	v_add_f32_e32 v32, 1.0, v32
	v_div_scale_f32 v33, s[14:15], v32, v32, v16
	v_rcp_f32_e32 v34, v33
	s_nop 0
	v_fma_f32 v35, -v33, v34, 1.0
	v_fmac_f32_e32 v34, v35, v34
	v_div_scale_f32 v35, vcc, v16, v32, v16
	v_mul_f32_e32 v36, v35, v34
	v_fma_f32 v37, -v33, v36, v35
	v_fmac_f32_e32 v36, v37, v34
	v_fma_f32 v33, -v33, v36, v35
	v_div_fmas_f32 v33, v33, v34, v36
	v_div_fixup_f32 v32, v33, v32, v16
	v_add_f32_e32 v16, v17, v68
	v_mul_f32_e32 v17, 0xbfb8aa3b, v16
	v_exp_f32_e32 v17, v17
	s_nop 0
	v_add_f32_e32 v17, 1.0, v17
	v_div_scale_f32 v33, s[14:15], v17, v17, v16
	v_rcp_f32_e32 v34, v33
	s_nop 0
	v_fma_f32 v35, -v33, v34, 1.0
	v_fmac_f32_e32 v34, v35, v34
	v_div_scale_f32 v35, vcc, v16, v17, v16
	v_mul_f32_e32 v36, v35, v34
	v_fma_f32 v37, -v33, v36, v35
	v_fmac_f32_e32 v36, v37, v34
	v_fma_f32 v33, -v33, v36, v35
	v_div_fmas_f32 v33, v33, v34, v36
	v_div_fixup_f32 v33, v33, v17, v16
	v_add_f32_e32 v16, v18, v68
	v_mul_f32_e32 v17, 0xbfb8aa3b, v16
	v_exp_f32_e32 v17, v17
	s_nop 0
	v_add_f32_e32 v17, 1.0, v17
	v_div_scale_f32 v18, s[14:15], v17, v17, v16
	v_rcp_f32_e32 v34, v18
	s_nop 0
	v_fma_f32 v35, -v18, v34, 1.0
	v_fmac_f32_e32 v34, v35, v34
	v_div_scale_f32 v35, vcc, v16, v17, v16
	v_mul_f32_e32 v36, v35, v34
	v_fma_f32 v37, -v18, v36, v35
	v_fmac_f32_e32 v36, v37, v34
	v_fma_f32 v18, -v18, v36, v35
	v_div_fmas_f32 v18, v18, v34, v36
	v_div_fixup_f32 v34, v18, v17, v16
	v_add_f32_e32 v16, v19, v68
	v_mul_f32_e32 v17, 0xbfb8aa3b, v16
	v_exp_f32_e32 v17, v17
	s_nop 0
	v_add_f32_e32 v17, 1.0, v17
	v_div_scale_f32 v18, s[14:15], v17, v17, v16
	v_rcp_f32_e32 v19, v18
	s_nop 0
	v_fma_f32 v35, -v18, v19, 1.0
	v_fmac_f32_e32 v19, v35, v19
	v_div_scale_f32 v35, vcc, v16, v17, v16
	v_mul_f32_e32 v36, v35, v19
	v_fma_f32 v37, -v18, v36, v35
	v_fmac_f32_e32 v36, v37, v19
	v_fma_f32 v18, -v18, v36, v35
	v_div_fmas_f32 v18, v18, v19, v36
	v_div_fixup_f32 v35, v18, v17, v16
	v_add_f32_e32 v16, v20, v68
	v_mul_f32_e32 v17, 0xbfb8aa3b, v16
	v_exp_f32_e32 v17, v17
	s_nop 0
	v_add_f32_e32 v17, 1.0, v17
	v_div_scale_f32 v18, s[14:15], v17, v17, v16
	v_rcp_f32_e32 v19, v18
	s_nop 0
	v_fma_f32 v20, -v18, v19, 1.0
	v_fmac_f32_e32 v19, v20, v19
	v_div_scale_f32 v20, vcc, v16, v17, v16
	v_mul_f32_e32 v36, v20, v19
; DI void compress_item(const Params& p, int L, int item, char* smem) {
;     ...
;         for (int i = 0; i < 16; ++i) {
;           const int rl = wm * 64 + mt * 32 + (i & 3) + 8 * (i >> 2) + 4 * hh;
;           const int n = nt * 32 + r;
;           float pb_ = 0.f;
; #pragma unroll
;           for (int q8 = 0; q8 < 8; ++q8) pb_ += p.pebias[(kv * 8 + q8) * 64 + n];
;           const float hsum = acc[mt][nt][i] + pb_;
;           Hs[rl * 65 + n] = hsum / (1.f + __expf(-hsum));
;         }
	v_fma_f32 v37, -v18, v36, v20
	v_fmac_f32_e32 v36, v37, v19
	v_fma_f32 v18, -v18, v36, v20
	v_div_fmas_f32 v18, v18, v19, v36
	v_div_fixup_f32 v36, v18, v17, v16
	v_add_f32_e32 v16, v21, v68
	v_mul_f32_e32 v17, 0xbfb8aa3b, v16
	v_exp_f32_e32 v17, v17
	s_nop 0
	v_add_f32_e32 v17, 1.0, v17
	v_div_scale_f32 v18, s[14:15], v17, v17, v16
	v_rcp_f32_e32 v19, v18
	s_nop 0
	v_fma_f32 v20, -v18, v19, 1.0
	v_fmac_f32_e32 v19, v20, v19
	v_div_scale_f32 v20, vcc, v16, v17, v16
	v_mul_f32_e32 v21, v20, v19
	v_fma_f32 v37, -v18, v21, v20
	v_fmac_f32_e32 v21, v37, v19
	v_fma_f32 v18, -v18, v21, v20
	v_div_fmas_f32 v18, v18, v19, v21
	v_div_fixup_f32 v21, v18, v17, v16
	v_add_f32_e32 v16, v22, v68
	v_mul_f32_e32 v17, 0xbfb8aa3b, v16
	v_exp_f32_e32 v17, v17
	s_nop 0
	v_add_f32_e32 v17, 1.0, v17
	v_div_scale_f32 v18, s[14:15], v17, v17, v16
	v_rcp_f32_e32 v19, v18
	s_nop 0
	v_fma_f32 v20, -v18, v19, 1.0
	v_fmac_f32_e32 v19, v20, v19
	v_div_scale_f32 v20, vcc, v16, v17, v16
	v_mul_f32_e32 v22, v20, v19
	v_fma_f32 v37, -v18, v22, v20
	v_fmac_f32_e32 v22, v37, v19
	v_fma_f32 v18, -v18, v22, v20
	v_div_fmas_f32 v18, v18, v19, v22
	v_div_fixup_f32 v22, v18, v17, v16
	v_add_f32_e32 v16, v23, v68
	v_mul_f32_e32 v17, 0xbfb8aa3b, v16
	v_exp_f32_e32 v17, v17
	s_nop 0
	v_add_f32_e32 v17, 1.0, v17
	v_div_scale_f32 v18, s[14:15], v17, v17, v16
	v_rcp_f32_e32 v19, v18
	s_nop 0
	v_fma_f32 v20, -v18, v19, 1.0
	v_fmac_f32_e32 v19, v20, v19
	v_div_scale_f32 v20, vcc, v16, v17, v16
	v_mul_f32_e32 v23, v20, v19
	v_fma_f32 v37, -v18, v23, v20
	v_fmac_f32_e32 v23, v37, v19
	v_fma_f32 v18, -v18, v23, v20
	v_div_fmas_f32 v18, v18, v19, v23
	v_div_fixup_f32 v23, v18, v17, v16
	v_add_f32_e32 v16, v24, v68
	v_mul_f32_e32 v17, 0xbfb8aa3b, v16
	v_exp_f32_e32 v17, v17
	s_nop 0
	v_add_f32_e32 v17, 1.0, v17
	v_div_scale_f32 v18, s[14:15], v17, v17, v16
	v_rcp_f32_e32 v19, v18
	s_nop 0
	v_fma_f32 v20, -v18, v19, 1.0
	v_fmac_f32_e32 v19, v20, v19
	v_div_scale_f32 v20, vcc, v16, v17, v16
	v_mul_f32_e32 v24, v20, v19
	v_fma_f32 v37, -v18, v24, v20
	v_fmac_f32_e32 v24, v37, v19
	v_fma_f32 v18, -v18, v24, v20
	v_div_fmas_f32 v18, v18, v19, v24
	v_div_fixup_f32 v24, v18, v17, v16
	v_add_f32_e32 v16, v25, v68
	v_mul_f32_e32 v17, 0xbfb8aa3b, v16
	v_exp_f32_e32 v17, v17
	s_nop 0
	v_add_f32_e32 v17, 1.0, v17
	v_div_scale_f32 v18, s[14:15], v17, v17, v16
	v_rcp_f32_e32 v19, v18
	s_nop 0
	v_fma_f32 v20, -v18, v19, 1.0
	v_fmac_f32_e32 v19, v20, v19
	v_div_scale_f32 v20, vcc, v16, v17, v16
	v_mul_f32_e32 v25, v20, v19
	v_fma_f32 v37, -v18, v25, v20
	v_fmac_f32_e32 v25, v37, v19
	v_fma_f32 v18, -v18, v25, v20
	v_div_fmas_f32 v18, v18, v19, v25
	v_div_fixup_f32 v25, v18, v17, v16
	v_add_f32_e32 v16, v26, v68
	v_mul_f32_e32 v17, 0xbfb8aa3b, v16
	v_exp_f32_e32 v17, v17
	s_nop 0
	v_add_f32_e32 v17, 1.0, v17
	v_div_scale_f32 v18, s[14:15], v17, v17, v16
	v_rcp_f32_e32 v19, v18
	s_nop 0
	v_fma_f32 v20, -v18, v19, 1.0
	v_fmac_f32_e32 v19, v20, v19
	v_div_scale_f32 v20, vcc, v16, v17, v16
	v_mul_f32_e32 v26, v20, v19
	v_fma_f32 v37, -v18, v26, v20
	v_fmac_f32_e32 v26, v37, v19
	v_fma_f32 v18, -v18, v26, v20
	v_div_fmas_f32 v18, v18, v19, v26
	v_div_fixup_f32 v26, v18, v17, v16
	v_add_f32_e32 v16, v27, v68
	v_mul_f32_e32 v17, 0xbfb8aa3b, v16
	v_exp_f32_e32 v17, v17
	s_nop 0
	v_add_f32_e32 v17, 1.0, v17
	v_div_scale_f32 v18, s[14:15], v17, v17, v16
	v_rcp_f32_e32 v19, v18
	s_nop 0
	v_fma_f32 v20, -v18, v19, 1.0
	v_fmac_f32_e32 v19, v20, v19
	v_div_scale_f32 v20, vcc, v16, v17, v16
	v_mul_f32_e32 v27, v20, v19
	v_fma_f32 v37, -v18, v27, v20
	v_fmac_f32_e32 v27, v37, v19
	v_fma_f32 v18, -v18, v27, v20
	v_div_fmas_f32 v18, v18, v19, v27
	v_div_fixup_f32 v20, v18, v17, v16
	v_add_f32_e32 v16, v28, v68
	v_mul_f32_e32 v17, 0xbfb8aa3b, v16
	v_exp_f32_e32 v17, v17
	s_nop 0
	v_add_f32_e32 v17, 1.0, v17
	v_div_scale_f32 v18, s[14:15], v17, v17, v16
	v_rcp_f32_e32 v19, v18
	s_nop 0
	v_fma_f32 v27, -v18, v19, 1.0
	v_fmac_f32_e32 v19, v27, v19
	v_div_scale_f32 v27, vcc, v16, v17, v16
	v_mul_f32_e32 v28, v27, v19
	v_fma_f32 v37, -v18, v28, v27
	v_fmac_f32_e32 v28, v37, v19
	v_fma_f32 v18, -v18, v28, v27
	v_div_fmas_f32 v18, v18, v19, v28
	v_div_fixup_f32 v19, v18, v17, v16
	v_add_f32_e32 v16, v29, v68
	v_mul_f32_e32 v17, 0xbfb8aa3b, v16
	v_exp_f32_e32 v17, v17
	s_nop 0
	v_add_f32_e32 v17, 1.0, v17
	v_div_scale_f32 v18, s[14:15], v17, v17, v16
	v_rcp_f32_e32 v27, v18
	s_nop 0
	v_fma_f32 v28, -v18, v27, 1.0
	v_fmac_f32_e32 v27, v28, v27
	v_div_scale_f32 v28, vcc, v16, v17, v16
	v_mul_f32_e32 v29, v28, v27
	v_fma_f32 v37, -v18, v29, v28
	v_fmac_f32_e32 v29, v37, v27
	v_fma_f32 v18, -v18, v29, v28
	v_div_fmas_f32 v18, v18, v27, v29
	v_div_fixup_f32 v18, v18, v17, v16
	v_add_f32_e32 v16, v30, v68
	v_mul_f32_e32 v17, 0xbfb8aa3b, v16
	v_exp_f32_e32 v17, v17
	s_nop 0
	v_add_f32_e32 v17, 1.0, v17
	v_div_scale_f32 v27, s[14:15], v17, v17, v16
	v_rcp_f32_e32 v28, v27
	s_nop 0
	v_fma_f32 v29, -v27, v28, 1.0
	v_fmac_f32_e32 v28, v29, v28
	v_div_scale_f32 v29, vcc, v16, v17, v16
	v_mul_f32_e32 v30, v29, v28
	v_fma_f32 v37, -v27, v30, v29
	v_fmac_f32_e32 v30, v37, v28
	v_fma_f32 v27, -v27, v30, v29
	v_div_fmas_f32 v27, v27, v28, v30
	v_div_fixup_f32 v17, v27, v17, v16
	v_add_f32_e32 v16, v31, v68
	v_mul_f32_e32 v27, 0xbfb8aa3b, v16
	v_exp_f32_e32 v27, v27
	s_nop 0
	v_add_f32_e32 v27, 1.0, v27
	v_div_scale_f32 v28, s[14:15], v27, v27, v16
	v_rcp_f32_e32 v29, v28
	s_nop 0
	v_fma_f32 v30, -v28, v29, 1.0
	v_fmac_f32_e32 v29, v30, v29
	v_div_scale_f32 v30, vcc, v16, v27, v16
	v_mul_f32_e32 v31, v30, v29
	v_fma_f32 v37, -v28, v31, v30
	v_fmac_f32_e32 v31, v37, v29
	v_fma_f32 v28, -v28, v31, v30
	v_div_fmas_f32 v28, v28, v29, v31
; DI void compress_item(const Params& p, int L, int item, char* smem) {
;     ...
;         for (int i = 0; i < 16; ++i) {
;           const int rl = wm * 64 + mt * 32 + (i & 3) + 8 * (i >> 2) + 4 * hh;
;           const int n = nt * 32 + r;
;           float pb_ = 0.f;
; #pragma unroll
;           for (int q8 = 0; q8 < 8; ++q8) pb_ += p.pebias[(kv * 8 + q8) * 64 + n];
;           const float hsum = acc[mt][nt][i] + pb_;
;           Hs[rl * 65 + n] = hsum / (1.f + __expf(-hsum));
;         }
	v_div_fixup_f32 v16, v28, v27, v16
	v_mul_f32_e32 v27, 0xbfb8aa3b, v0
	v_exp_f32_e32 v27, v27
	s_nop 0
	v_add_f32_e32 v27, 1.0, v27
	v_div_scale_f32 v28, s[14:15], v27, v27, v0
	v_rcp_f32_e32 v29, v28
	s_nop 0
	v_fma_f32 v30, -v28, v29, 1.0
	v_fmac_f32_e32 v29, v30, v29
	v_div_scale_f32 v30, vcc, v0, v27, v0
	v_mul_f32_e32 v31, v30, v29
	v_fma_f32 v37, -v28, v31, v30
	v_fmac_f32_e32 v31, v37, v29
	v_fma_f32 v28, -v28, v31, v30
	v_div_fmas_f32 v28, v28, v29, v31
	v_div_fixup_f32 v0, v28, v27, v0
	v_add_u32_e32 v27, 0x2000, v66
	ds_write2_b32 v27, v32, v0 offset0:32 offset1:64
	v_add_f32_e32 v0, v1, v57
	v_mul_f32_e32 v1, 0xbfb8aa3b, v0
	v_exp_f32_e32 v1, v1
	s_nop 0
	v_add_f32_e32 v1, 1.0, v1
	v_div_scale_f32 v28, s[14:15], v1, v1, v0
	v_rcp_f32_e32 v29, v28
	s_nop 0
	v_fma_f32 v30, -v28, v29, 1.0
	v_fmac_f32_e32 v29, v30, v29
	v_div_scale_f32 v30, vcc, v0, v1, v0
	v_mul_f32_e32 v31, v30, v29
	v_fma_f32 v32, -v28, v31, v30
	v_fmac_f32_e32 v31, v32, v29
	v_fma_f32 v28, -v28, v31, v30
	v_div_fmas_f32 v28, v28, v29, v31
	v_div_fixup_f32 v0, v28, v1, v0
	ds_write2_b32 v27, v33, v0 offset0:97 offset1:129
	v_add_f32_e32 v0, v2, v57
	v_mul_f32_e32 v1, 0xbfb8aa3b, v0
	v_exp_f32_e32 v1, v1
	s_nop 0
	v_add_f32_e32 v1, 1.0, v1
	v_div_scale_f32 v2, s[14:15], v1, v1, v0
	v_rcp_f32_e32 v28, v2
	s_nop 0
	v_fma_f32 v29, -v2, v28, 1.0
	v_fmac_f32_e32 v28, v29, v28
	v_div_scale_f32 v29, vcc, v0, v1, v0
	v_mul_f32_e32 v30, v29, v28
	v_fma_f32 v31, -v2, v30, v29
	v_fmac_f32_e32 v30, v31, v28
	v_fma_f32 v2, -v2, v30, v29
	v_div_fmas_f32 v2, v2, v28, v30
	v_div_fixup_f32 v0, v2, v1, v0
	ds_write2_b32 v27, v34, v0 offset0:162 offset1:194
	v_add_f32_e32 v0, v3, v57
	v_mul_f32_e32 v1, 0xbfb8aa3b, v0
	v_exp_f32_e32 v1, v1
	s_nop 0
	v_add_f32_e32 v1, 1.0, v1
	v_div_scale_f32 v2, s[14:15], v1, v1, v0
	v_rcp_f32_e32 v3, v2
	s_nop 0
	v_fma_f32 v27, -v2, v3, 1.0
	v_fmac_f32_e32 v3, v27, v3
	v_div_scale_f32 v27, vcc, v0, v1, v0
	v_mul_f32_e32 v28, v27, v3
	v_fma_f32 v29, -v2, v28, v27
	v_fmac_f32_e32 v28, v29, v3
	v_fma_f32 v2, -v2, v28, v27
	v_div_fmas_f32 v2, v2, v3, v28
	v_div_fixup_f32 v0, v2, v1, v0
	v_add_u32_e32 v1, 0x2200, v66
	ds_write2_b32 v1, v35, v0 offset0:99 offset1:131
	v_add_f32_e32 v0, v4, v57
	v_mul_f32_e32 v1, 0xbfb8aa3b, v0
	v_exp_f32_e32 v1, v1
	s_nop 0
	v_add_f32_e32 v1, 1.0, v1
	v_div_scale_f32 v2, s[14:15], v1, v1, v0
	v_rcp_f32_e32 v3, v2
	s_nop 0
	v_fma_f32 v4, -v2, v3, 1.0
	v_fmac_f32_e32 v3, v4, v3
	v_div_scale_f32 v4, vcc, v0, v1, v0
	v_mul_f32_e32 v27, v4, v3
	v_fma_f32 v28, -v2, v27, v4
	v_fmac_f32_e32 v27, v28, v3
	v_fma_f32 v2, -v2, v27, v4
	v_div_fmas_f32 v2, v2, v3, v27
	v_div_fixup_f32 v0, v2, v1, v0
	v_add_u32_e32 v1, 0x2800, v66
	ds_write2_b32 v1, v36, v0 offset0:40 offset1:72
	v_add_f32_e32 v0, v5, v57
	v_mul_f32_e32 v2, 0xbfb8aa3b, v0
	v_exp_f32_e32 v2, v2
	s_nop 0
	v_add_f32_e32 v2, 1.0, v2
	v_div_scale_f32 v3, s[14:15], v2, v2, v0
	v_rcp_f32_e32 v4, v3
	s_nop 0
	v_fma_f32 v5, -v3, v4, 1.0
	v_fmac_f32_e32 v4, v5, v4
	v_div_scale_f32 v5, vcc, v0, v2, v0
	v_mul_f32_e32 v27, v5, v4
	v_fma_f32 v28, -v3, v27, v5
	v_fmac_f32_e32 v27, v28, v4
	v_fma_f32 v3, -v3, v27, v5
	v_div_fmas_f32 v3, v3, v4, v27
	v_div_fixup_f32 v0, v3, v2, v0
	ds_write2_b32 v1, v21, v0 offset0:105 offset1:137
	v_add_f32_e32 v0, v6, v57
	v_mul_f32_e32 v2, 0xbfb8aa3b, v0
	v_exp_f32_e32 v2, v2
	s_nop 0
	v_add_f32_e32 v2, 1.0, v2
	v_div_scale_f32 v3, s[14:15], v2, v2, v0
	v_rcp_f32_e32 v4, v3
	s_nop 0
	v_fma_f32 v5, -v3, v4, 1.0
	v_fmac_f32_e32 v4, v5, v4
	v_div_scale_f32 v5, vcc, v0, v2, v0
	v_mul_f32_e32 v6, v5, v4
	v_fma_f32 v21, -v3, v6, v5
	v_fmac_f32_e32 v6, v21, v4
	v_fma_f32 v3, -v3, v6, v5
	v_div_fmas_f32 v3, v3, v4, v6
	v_div_fixup_f32 v0, v3, v2, v0
	ds_write2_b32 v1, v22, v0 offset0:170 offset1:202
	v_add_f32_e32 v0, v7, v57
	v_mul_f32_e32 v1, 0xbfb8aa3b, v0
	v_exp_f32_e32 v1, v1
	s_nop 0
	v_add_f32_e32 v1, 1.0, v1
	v_div_scale_f32 v2, s[14:15], v1, v1, v0
	v_rcp_f32_e32 v3, v2
	s_nop 0
	v_fma_f32 v4, -v2, v3, 1.0
	v_fmac_f32_e32 v3, v4, v3
	v_div_scale_f32 v4, vcc, v0, v1, v0
	v_mul_f32_e32 v5, v4, v3
	v_fma_f32 v6, -v2, v5, v4
	v_fmac_f32_e32 v5, v6, v3
	v_fma_f32 v2, -v2, v5, v4
	v_div_fmas_f32 v2, v2, v3, v5
	v_div_fixup_f32 v0, v2, v1, v0
	v_add_u32_e32 v1, 0x2a00, v66
	ds_write2_b32 v1, v23, v0 offset0:107 offset1:139
	v_add_f32_e32 v0, v8, v57
	v_mul_f32_e32 v1, 0xbfb8aa3b, v0
	v_exp_f32_e32 v1, v1
	s_nop 0
	v_add_f32_e32 v1, 1.0, v1
	v_div_scale_f32 v2, s[14:15], v1, v1, v0
	v_rcp_f32_e32 v3, v2
	s_nop 0
	v_fma_f32 v4, -v2, v3, 1.0
	v_fmac_f32_e32 v3, v4, v3
	v_div_scale_f32 v4, vcc, v0, v1, v0
	v_mul_f32_e32 v5, v4, v3
	v_fma_f32 v6, -v2, v5, v4
	v_fmac_f32_e32 v5, v6, v3
	v_fma_f32 v2, -v2, v5, v4
	v_div_fmas_f32 v2, v2, v3, v5
	v_div_fixup_f32 v0, v2, v1, v0
	v_add_u32_e32 v1, 0x3000, v66
	ds_write2_b32 v1, v24, v0 offset0:48 offset1:80
	v_add_f32_e32 v0, v9, v57
	v_mul_f32_e32 v2, 0xbfb8aa3b, v0
	v_exp_f32_e32 v2, v2
	s_nop 0
	v_add_f32_e32 v2, 1.0, v2
	v_div_scale_f32 v3, s[14:15], v2, v2, v0
	v_rcp_f32_e32 v4, v3
	s_nop 0
	v_fma_f32 v5, -v3, v4, 1.0
	v_fmac_f32_e32 v4, v5, v4
	v_div_scale_f32 v5, vcc, v0, v2, v0
	v_mul_f32_e32 v6, v5, v4
	v_fma_f32 v7, -v3, v6, v5
	v_fmac_f32_e32 v6, v7, v4
	v_fma_f32 v3, -v3, v6, v5
	v_div_fmas_f32 v3, v3, v4, v6
	v_div_fixup_f32 v0, v3, v2, v0
	ds_write2_b32 v1, v25, v0 offset0:113 offset1:145
	v_add_f32_e32 v0, v10, v57
	v_mul_f32_e32 v2, 0xbfb8aa3b, v0
	v_exp_f32_e32 v2, v2
	s_nop 0
	v_add_f32_e32 v2, 1.0, v2
	v_div_scale_f32 v3, s[14:15], v2, v2, v0
	v_rcp_f32_e32 v4, v3
	s_nop 0
	v_fma_f32 v5, -v3, v4, 1.0
	v_fmac_f32_e32 v4, v5, v4
	v_div_scale_f32 v5, vcc, v0, v2, v0
	v_mul_f32_e32 v6, v5, v4
	v_fma_f32 v7, -v3, v6, v5
	v_fmac_f32_e32 v6, v7, v4
	v_fma_f32 v3, -v3, v6, v5
	v_div_fmas_f32 v3, v3, v4, v6
	v_div_fixup_f32 v0, v3, v2, v0
	ds_write2_b32 v1, v26, v0 offset0:178 offset1:210
	v_mov_b32_e32 v0, v83
	v_mov_b32_e32 v1, v85
	s_waitcnt vmcnt(1)
; DI void compress_item(const Params& p, int L, int item, char* smem) {
;     ...
;         for (int i = 0; i < 16; ++i) {
;           const int rl = wm * 64 + mt * 32 + (i & 3) + 8 * (i >> 2) + 4 * hh;
;           const int n = nt * 32 + r;
;           float pb_ = 0.f;
; #pragma unroll
;           for (int q8 = 0; q8 < 8; ++q8) pb_ += p.pebias[(kv * 8 + q8) * 64 + n];
;           const float hsum = acc[mt][nt][i] + pb_;
;           Hs[rl * 65 + n] = hsum / (1.f + __expf(-hsum));
;         }
	v_add_f32_e32 v2, v48, v0
	s_waitcnt vmcnt(0)
	v_add_f32_e32 v3, v2, v1
	v_mov_b32_e32 v2, v87
	s_waitcnt vmcnt(0)
	v_add_f32_e32 v4, v3, v2
	v_mov_b32_e32 v3, v89
	s_waitcnt vmcnt(0)
	v_add_f32_e32 v5, v4, v3
	v_mov_b32_e32 v4, v91
	s_waitcnt vmcnt(0)
	v_add_f32_e32 v5, v5, v4
	v_add_f32_e32 v5, v11, v5
	v_mul_f32_e32 v6, 0xbfb8aa3b, v5
	v_exp_f32_e32 v6, v6
	s_nop 0
	v_add_f32_e32 v6, 1.0, v6
	v_div_scale_f32 v7, s[14:15], v6, v6, v5
	v_rcp_f32_e32 v8, v7
	s_nop 0
	v_fma_f32 v9, -v7, v8, 1.0
	v_fmac_f32_e32 v8, v9, v8
	v_div_scale_f32 v9, vcc, v5, v6, v5
	v_mul_f32_e32 v10, v9, v8
	v_fma_f32 v11, -v7, v10, v9
	v_fmac_f32_e32 v10, v11, v8
	v_fma_f32 v7, -v7, v10, v9
	v_div_fmas_f32 v7, v7, v8, v10
	v_div_fixup_f32 v5, v7, v6, v5
	v_add_u32_e32 v6, 0x3200, v66
	ds_write2_b32 v6, v20, v5 offset0:115 offset1:147
	v_mov_b32_e32 v5, v77
	v_mov_b32_e32 v6, v79
	s_waitcnt vmcnt(1)
	v_add_f32_e32 v5, 0, v5
	s_waitcnt vmcnt(0)
	v_add_f32_e32 v5, v5, v6
	v_mov_b32_e32 v6, v81
	s_waitcnt vmcnt(0)
	v_add_f32_e32 v5, v5, v6
	v_add_f32_e32 v0, v5, v0
	v_add_f32_e32 v0, v0, v1
	v_add_f32_e32 v0, v0, v2
	v_add_f32_e32 v0, v0, v3
	v_add_f32_e32 v0, v0, v4
	v_add_f32_e32 v1, v12, v0
	v_mul_f32_e32 v2, 0xbfb8aa3b, v1
	v_exp_f32_e32 v2, v2
	s_nop 0
	v_add_f32_e32 v2, 1.0, v2
	v_div_scale_f32 v3, s[14:15], v2, v2, v1
	v_rcp_f32_e32 v4, v3
	s_nop 0
	v_fma_f32 v5, -v3, v4, 1.0
	v_fmac_f32_e32 v4, v5, v4
	v_div_scale_f32 v5, vcc, v1, v2, v1
	v_mul_f32_e32 v6, v5, v4
	v_fma_f32 v7, -v3, v6, v5
	v_fmac_f32_e32 v6, v7, v4
	v_fma_f32 v3, -v3, v6, v5
	v_div_fmas_f32 v3, v3, v4, v6
	v_div_fixup_f32 v1, v3, v2, v1
	v_add_u32_e32 v2, 0x3800, v66
	ds_write2_b32 v2, v19, v1 offset0:56 offset1:88
	v_add_f32_e32 v1, v13, v0
	v_mul_f32_e32 v3, 0xbfb8aa3b, v1
	v_exp_f32_e32 v3, v3
	s_nop 0
	v_add_f32_e32 v3, 1.0, v3
	v_div_scale_f32 v4, s[14:15], v3, v3, v1
	v_rcp_f32_e32 v5, v4
	s_nop 0
	v_fma_f32 v6, -v4, v5, 1.0
	v_fmac_f32_e32 v5, v6, v5
	v_div_scale_f32 v6, vcc, v1, v3, v1
	v_mul_f32_e32 v7, v6, v5
	v_fma_f32 v8, -v4, v7, v6
	v_fmac_f32_e32 v7, v8, v5
	v_fma_f32 v4, -v4, v7, v6
	v_div_fmas_f32 v4, v4, v5, v7
	v_div_fixup_f32 v1, v4, v3, v1
	ds_write2_b32 v2, v18, v1 offset0:121 offset1:153
	v_add_f32_e32 v1, v14, v0
	v_mul_f32_e32 v3, 0xbfb8aa3b, v1
	v_exp_f32_e32 v3, v3
	v_add_f32_e32 v0, v15, v0
	v_add_f32_e32 v3, 1.0, v3
	v_div_scale_f32 v4, s[14:15], v3, v3, v1
	v_rcp_f32_e32 v5, v4
	s_nop 0
	v_fma_f32 v6, -v4, v5, 1.0
	v_fmac_f32_e32 v5, v6, v5
	v_div_scale_f32 v6, vcc, v1, v3, v1
	v_mul_f32_e32 v7, v6, v5
	v_fma_f32 v8, -v4, v7, v6
	v_fmac_f32_e32 v7, v8, v5
	v_fma_f32 v4, -v4, v7, v6
	v_div_fmas_f32 v4, v4, v5, v7
	v_div_fixup_f32 v1, v4, v3, v1
	ds_write2_b32 v2, v17, v1 offset0:186 offset1:218
	v_mul_f32_e32 v1, 0xbfb8aa3b, v0
	v_exp_f32_e32 v1, v1
	s_nop 0
	v_add_f32_e32 v1, 1.0, v1
	v_div_scale_f32 v2, s[14:15], v1, v1, v0
	v_rcp_f32_e32 v3, v2
	s_nop 0
	v_fma_f32 v4, -v2, v3, 1.0
	v_fmac_f32_e32 v3, v4, v3
	v_div_scale_f32 v4, vcc, v0, v1, v0
	v_mul_f32_e32 v5, v4, v3
	v_fma_f32 v6, -v2, v5, v4
	v_fmac_f32_e32 v5, v6, v3
	v_fma_f32 v2, -v2, v5, v4
	v_div_fmas_f32 v2, v2, v3, v5
	v_div_fixup_f32 v0, v2, v1, v0
	v_add_u32_e32 v1, 0x3a00, v66
	ds_write2_b32 v1, v16, v0 offset0:123 offset1:155
